# up epilogue H stores use cache policy 'sc1' instead of nt (test of L2 write-path behaviour), on top of the K-loop edits
# baseline (speedup 1.0000x reference)
; __device__ __forceinline__ unsigned cvt_pk_bf16(float lo, float hi) { unsigned r; asm volatile("v_cvt_pk_bf16_f32 %0, %1, %2" : "=v"(r) : "v"(lo), "v"(hi)); return r; }
;     __device__ __forceinline__ void operator()(const f32x4 (&acc)[2][2][4][2], const Unit& u, int ui, int wr, int wc, int fr, int fq) const {
;     ...
;         const int row0 = u.pm * BM + wr * 64 + fr, col0 = u.pn * HALF + wc * 32 + 8 * fq;
;         float rs[2][4];
; #pragma unroll
;         for (int ai = 0; ai < 2; ++ai)
; #pragma unroll
;             for (int m = 0; m < 4; ++m) rs[ai][m] = row_rstd(lds, ui, ai * HALF + wr * 64 + m * 16 + fr);
; #pragma unroll
;         for (int ai = 0; ai < 2; ++ai)
; #pragma unroll
;             for (int m = 0; m < 4; ++m) { const float r = rs[ai][m]; const int row = row0 + ai * HALF + m * 16;
;                 const float c1 = r * -1.44269504089f, r2 = r * r; u32x4 w;
; #pragma unroll
;                 for (int n = 0; n < 2; ++n)
; #pragma unroll
;                     for (int p = 0; p < 2; ++p) { const f32x2 g = (f32x2){acc[ai][0][m][n][2 * p], acc[ai][0][m][n][2 * p + 1]}, uu = (f32x2){acc[ai][1][m][n][2 * p], acc[ai][1][m][n][2 * p + 1]};
;                         const f32x2 t = g * c1; f32x2 d; d.x = __builtin_amdgcn_exp2f(t.x); d.y = __builtin_amdgcn_exp2f(t.y); d = d + 1.0f;
;                         f32x2 q; q.x = __builtin_amdgcn_rcpf(d.x); q.y = __builtin_amdgcn_rcpf(d.y);
;                         const f32x2 hh = (g * uu) * (q * r2); w[2 * n + p] = cvt_pk_bf16(hh.x, hh.y); }
;                 __builtin_nontemporal_store(w, (u32x4*)(H + (size_t)row * ldh + col0)); }
.LBB0_449:
	v_mov_b32_e32 v140, v147
	v_mov_b32_e32 v167, v164
	v_pk_mul_f32 v[120:121], v[124:125], v[120:121]
	v_add_u32_e32 v171, s35, v140
	v_lshlrev_b32_e32 v140, 2, v171
	v_lshl_add_u32 v140, s48, 10, v140
	v_add_u32_e32 v140, 0x20400, v140
	ds_read2_b32 v[168:169], v140 offset1:16
	ds_read2_b32 v[162:163], v140 offset0:32 offset1:48
	ds_read2_b32 v[142:143], v140 offset0:128 offset1:144
	ds_read2_b32 v[140:141], v140 offset0:160 offset1:176
	v_pk_mul_f32 v[122:123], v[126:127], v[122:123]
	s_waitcnt lgkmcnt(0)
	v_mul_f32_e32 v172, 0xbfb8aa3b, v168
	v_pk_mul_f32 v[174:175], v[124:125], v[172:173] op_sel_hi:[1,0]
	v_pk_mul_f32 v[124:125], v[126:127], v[172:173] op_sel_hi:[1,0]
	v_exp_f32_e32 v174, v174
	v_exp_f32_e32 v175, v175
	v_exp_f32_e32 v124, v124
	v_exp_f32_e32 v125, v125
	v_mul_f32_e32 v168, v168, v168
	v_pk_add_f32 v[174:175], v[174:175], 1.0 op_sel_hi:[1,0]
	v_pk_mul_f32 v[112:113], v[116:117], v[112:113]
	v_rcp_f32_e32 v174, v174
	v_rcp_f32_e32 v175, v175
	v_pk_add_f32 v[124:125], v[124:125], 1.0 op_sel_hi:[1,0]
	v_pk_mul_f32 v[114:115], v[118:119], v[114:115]
	v_rcp_f32_e32 v124, v124
	v_rcp_f32_e32 v125, v125
	v_pk_mul_f32 v[126:127], v[168:169], v[174:175] op_sel_hi:[0,1]
	v_pk_mul_f32 v[120:121], v[120:121], v[126:127]
	v_pk_mul_f32 v[126:127], v[116:117], v[172:173] op_sel_hi:[1,0]
	v_pk_mul_f32 v[124:125], v[168:169], v[124:125] op_sel_hi:[0,1]
	v_exp_f32_e32 v126, v126
	v_exp_f32_e32 v127, v127
	v_pk_mul_f32 v[122:123], v[122:123], v[124:125]
	v_pk_mul_f32 v[124:125], v[118:119], v[172:173] op_sel_hi:[1,0]
	v_cvt_pk_bf16_f32 v120, v120, v121
	v_cvt_pk_bf16_f32 v121, v122, v123
	v_pk_add_f32 v[122:123], v[126:127], 1.0 op_sel_hi:[1,0]
	v_exp_f32_e32 v124, v124
	v_exp_f32_e32 v125, v125
	v_rcp_f32_e32 v122, v122
	v_rcp_f32_e32 v123, v123
	s_lshl_b32 s5, s47, 7
	v_pk_add_f32 v[116:117], v[124:125], 1.0 op_sel_hi:[1,0]
	s_or_b32 s5, s5, s36
	v_rcp_f32_e32 v116, v116
	v_rcp_f32_e32 v117, v117
	v_pk_mul_f32 v[118:119], v[168:169], v[122:123] op_sel_hi:[0,1]
	v_pk_mul_f32 v[112:113], v[112:113], v[118:119]
	v_mul_f32_e32 v118, 0xbfb8aa3b, v169
	v_cvt_pk_bf16_f32 v122, v112, v113
	v_pk_mul_f32 v[112:113], v[168:169], v[116:117] op_sel_hi:[0,1]
	v_pk_mul_f32 v[124:125], v[108:109], v[118:119] op_sel_hi:[1,0]
	v_lshl_add_u32 v170, v167, 3, s5
	v_pk_mul_f32 v[112:113], v[114:115], v[112:113]
	v_exp_f32_e32 v124, v124
	v_exp_f32_e32 v125, v125
	v_lshl_add_u32 v167, s46, 8, v171
	v_ashrrev_i32_e32 v171, 31, v170
	v_cvt_pk_bf16_f32 v123, v112, v113
	v_mov_b64_e32 v[112:113], s[20:21]
	v_pk_mul_f32 v[104:105], v[108:109], v[104:105]
	v_pk_mul_f32 v[108:109], v[110:111], v[118:119] op_sel_hi:[1,0]
	v_mad_i64_i32 v[116:117], s[14:15], v167, s59, v[112:113]
	v_lshlrev_b64 v[114:115], 1, v[170:171]
	v_exp_f32_e32 v108, v108
	v_exp_f32_e32 v109, v109
	v_lshl_add_u64 v[116:117], v[116:117], 0, v[114:115]
	global_store_dwordx4 v[116:117], v[120:123], off sc1
	v_mul_f32_e32 v116, v169, v169
	v_pk_add_f32 v[108:109], v[108:109], 1.0 op_sel_hi:[1,0]
	v_pk_add_f32 v[120:121], v[124:125], 1.0 op_sel_hi:[1,0]
	v_rcp_f32_e32 v108, v108
	v_rcp_f32_e32 v120, v120
	v_rcp_f32_e32 v121, v121
	v_rcp_f32_e32 v109, v109
	v_pk_mul_f32 v[106:107], v[110:111], v[106:107]
	v_pk_mul_f32 v[96:97], v[100:101], v[96:97]
	v_pk_mul_f32 v[110:111], v[116:117], v[120:121] op_sel_hi:[0,1]
	v_pk_mul_f32 v[104:105], v[104:105], v[110:111]
	v_pk_mul_f32 v[110:111], v[100:101], v[118:119] op_sel_hi:[1,0]
	v_pk_mul_f32 v[108:109], v[116:117], v[108:109] op_sel_hi:[0,1]
	v_exp_f32_e32 v110, v110
	v_exp_f32_e32 v111, v111
	v_pk_mul_f32 v[106:107], v[106:107], v[108:109]
	v_pk_mul_f32 v[108:109], v[102:103], v[118:119] op_sel_hi:[1,0]
	v_cvt_pk_bf16_f32 v104, v104, v105
	v_cvt_pk_bf16_f32 v105, v106, v107
	v_pk_add_f32 v[106:107], v[110:111], 1.0 op_sel_hi:[1,0]
	v_exp_f32_e32 v108, v108
	v_exp_f32_e32 v109, v109
	v_rcp_f32_e32 v106, v106
	v_rcp_f32_e32 v107, v107
	v_pk_mul_f32 v[98:99], v[102:103], v[98:99]
	v_pk_add_f32 v[100:101], v[108:109], 1.0 op_sel_hi:[1,0]
	v_pk_mul_f32 v[88:89], v[92:93], v[88:89]
	v_rcp_f32_e32 v100, v100
	v_rcp_f32_e32 v101, v101
	v_pk_mul_f32 v[102:103], v[116:117], v[106:107] op_sel_hi:[0,1]
	v_pk_mul_f32 v[96:97], v[96:97], v[102:103]
	v_pk_mul_f32 v[90:91], v[94:95], v[90:91]
	v_cvt_pk_bf16_f32 v106, v96, v97
	v_pk_mul_f32 v[96:97], v[116:117], v[100:101] op_sel_hi:[0,1]
	v_pk_mul_f32 v[96:97], v[98:99], v[96:97]
	v_mul_f32_e32 v98, 0xbfb8aa3b, v162
	v_pk_mul_f32 v[100:101], v[92:93], v[98:99] op_sel_hi:[1,0]
	v_pk_mul_f32 v[92:93], v[94:95], v[98:99] op_sel_hi:[1,0]
	v_exp_f32_e32 v100, v100
	v_exp_f32_e32 v101, v101
	v_exp_f32_e32 v92, v92
	v_exp_f32_e32 v93, v93
	v_cvt_pk_bf16_f32 v107, v96, v97
	v_pk_add_f32 v[100:101], v[100:101], 1.0 op_sel_hi:[1,0]
	v_add_u32_e32 v96, 16, v167
	v_rcp_f32_e32 v100, v100
	v_rcp_f32_e32 v101, v101
	v_mad_i64_i32 v[96:97], s[14:15], v96, s59, v[112:113]
	v_pk_add_f32 v[92:93], v[92:93], 1.0 op_sel_hi:[1,0]
	v_lshl_add_u64 v[96:97], v[96:97], 0, v[114:115]
	v_rcp_f32_e32 v92, v92
	v_rcp_f32_e32 v93, v93
	global_store_dwordx4 v[96:97], v[104:107], off sc1
	v_mul_f32_e32 v96, v162, v162
	v_pk_mul_f32 v[94:95], v[96:97], v[100:101] op_sel_hi:[0,1]
	v_pk_mul_f32 v[88:89], v[88:89], v[94:95]
	v_pk_mul_f32 v[94:95], v[84:85], v[98:99] op_sel_hi:[1,0]
	v_pk_mul_f32 v[92:93], v[96:97], v[92:93] op_sel_hi:[0,1]
	v_exp_f32_e32 v94, v94
	v_exp_f32_e32 v95, v95
	v_pk_mul_f32 v[90:91], v[90:91], v[92:93]
	v_pk_mul_f32 v[92:93], v[86:87], v[98:99] op_sel_hi:[1,0]
	v_cvt_pk_bf16_f32 v88, v88, v89
	v_cvt_pk_bf16_f32 v89, v90, v91
	v_pk_add_f32 v[90:91], v[94:95], 1.0 op_sel_hi:[1,0]
	v_exp_f32_e32 v92, v92
; __device__ __forceinline__ unsigned cvt_pk_bf16(float lo, float hi) { unsigned r; asm volatile("v_cvt_pk_bf16_f32 %0, %1, %2" : "=v"(r) : "v"(lo), "v"(hi)); return r; }
;     __device__ __forceinline__ void operator()(const f32x4 (&acc)[2][2][4][2], const Unit& u, int ui, int wr, int wc, int fr, int fq) const {
;     ...
;             for (int m = 0; m < 4; ++m) { const float r = rs[ai][m]; const int row = row0 + ai * HALF + m * 16;
;                 const float c1 = r * -1.44269504089f, r2 = r * r; u32x4 w;
; #pragma unroll
;                 for (int n = 0; n < 2; ++n)
; #pragma unroll
;                     for (int p = 0; p < 2; ++p) { const f32x2 g = (f32x2){acc[ai][0][m][n][2 * p], acc[ai][0][m][n][2 * p + 1]}, uu = (f32x2){acc[ai][1][m][n][2 * p], acc[ai][1][m][n][2 * p + 1]};
;                         const f32x2 t = g * c1; f32x2 d; d.x = __builtin_amdgcn_exp2f(t.x); d.y = __builtin_amdgcn_exp2f(t.y); d = d + 1.0f;
;                         f32x2 q; q.x = __builtin_amdgcn_rcpf(d.x); q.y = __builtin_amdgcn_rcpf(d.y);
;                         const f32x2 hh = (g * uu) * (q * r2); w[2 * n + p] = cvt_pk_bf16(hh.x, hh.y); }
;                 __builtin_nontemporal_store(w, (u32x4*)(H + (size_t)row * ldh + col0)); }
	v_exp_f32_e32 v93, v93
	v_rcp_f32_e32 v90, v90
	v_rcp_f32_e32 v91, v91
	v_pk_mul_f32 v[80:81], v[84:85], v[80:81]
	v_pk_add_f32 v[84:85], v[92:93], 1.0 op_sel_hi:[1,0]
	v_pk_mul_f32 v[82:83], v[86:87], v[82:83]
	v_rcp_f32_e32 v84, v84
	v_rcp_f32_e32 v85, v85
	v_pk_mul_f32 v[86:87], v[96:97], v[90:91] op_sel_hi:[0,1]
	v_pk_mul_f32 v[80:81], v[80:81], v[86:87]
	v_pk_mul_f32 v[72:73], v[76:77], v[72:73]
	v_cvt_pk_bf16_f32 v90, v80, v81
	v_pk_mul_f32 v[80:81], v[96:97], v[84:85] op_sel_hi:[0,1]
	v_pk_mul_f32 v[80:81], v[82:83], v[80:81]
	v_mul_f32_e32 v82, 0xbfb8aa3b, v163
	v_pk_mul_f32 v[84:85], v[76:77], v[82:83] op_sel_hi:[1,0]
	v_pk_mul_f32 v[76:77], v[78:79], v[82:83] op_sel_hi:[1,0]
	v_exp_f32_e32 v84, v84
	v_exp_f32_e32 v85, v85
	v_exp_f32_e32 v76, v76
	v_exp_f32_e32 v77, v77
	v_cvt_pk_bf16_f32 v91, v80, v81
	v_pk_add_f32 v[84:85], v[84:85], 1.0 op_sel_hi:[1,0]
	v_add_u32_e32 v80, 32, v167
	v_rcp_f32_e32 v84, v84
	v_rcp_f32_e32 v85, v85
	v_mad_i64_i32 v[80:81], s[14:15], v80, s59, v[112:113]
	v_pk_add_f32 v[76:77], v[76:77], 1.0 op_sel_hi:[1,0]
	v_lshl_add_u64 v[80:81], v[80:81], 0, v[114:115]
	v_rcp_f32_e32 v76, v76
	v_rcp_f32_e32 v77, v77
	global_store_dwordx4 v[80:81], v[88:91], off sc1
	v_mul_f32_e32 v80, v163, v163
	v_pk_mul_f32 v[74:75], v[78:79], v[74:75]
	v_pk_mul_f32 v[78:79], v[80:81], v[84:85] op_sel_hi:[0,1]
	v_pk_mul_f32 v[72:73], v[72:73], v[78:79]
	v_pk_mul_f32 v[78:79], v[68:69], v[82:83] op_sel_hi:[1,0]
	v_pk_mul_f32 v[76:77], v[80:81], v[76:77] op_sel_hi:[0,1]
	v_exp_f32_e32 v78, v78
	v_exp_f32_e32 v79, v79
	v_pk_mul_f32 v[74:75], v[74:75], v[76:77]
	v_pk_mul_f32 v[76:77], v[70:71], v[82:83] op_sel_hi:[1,0]
	v_cvt_pk_bf16_f32 v72, v72, v73
	v_cvt_pk_bf16_f32 v73, v74, v75
	v_pk_add_f32 v[74:75], v[78:79], 1.0 op_sel_hi:[1,0]
	v_exp_f32_e32 v76, v76
	v_exp_f32_e32 v77, v77
	v_rcp_f32_e32 v74, v74
	v_rcp_f32_e32 v75, v75
	v_pk_mul_f32 v[64:65], v[68:69], v[64:65]
	v_pk_add_f32 v[68:69], v[76:77], 1.0 op_sel_hi:[1,0]
	v_pk_mul_f32 v[66:67], v[70:71], v[66:67]
	v_rcp_f32_e32 v68, v68
	v_rcp_f32_e32 v69, v69
	v_pk_mul_f32 v[70:71], v[80:81], v[74:75] op_sel_hi:[0,1]
	v_pk_mul_f32 v[64:65], v[64:65], v[70:71]
	v_pk_mul_f32 v[56:57], v[60:61], v[56:57]
	v_cvt_pk_bf16_f32 v74, v64, v65
	v_pk_mul_f32 v[64:65], v[80:81], v[68:69] op_sel_hi:[0,1]
	v_pk_mul_f32 v[64:65], v[66:67], v[64:65]
	v_mul_f32_e32 v66, 0xbfb8aa3b, v142
	v_pk_mul_f32 v[68:69], v[60:61], v[66:67] op_sel_hi:[1,0]
	v_pk_mul_f32 v[60:61], v[62:63], v[66:67] op_sel_hi:[1,0]
	v_exp_f32_e32 v68, v68
	v_exp_f32_e32 v69, v69
	v_exp_f32_e32 v60, v60
	v_exp_f32_e32 v61, v61
	v_cvt_pk_bf16_f32 v75, v64, v65
	v_pk_add_f32 v[68:69], v[68:69], 1.0 op_sel_hi:[1,0]
	v_add_u32_e32 v64, 48, v167
	v_rcp_f32_e32 v68, v68
	v_rcp_f32_e32 v69, v69
	v_mad_i64_i32 v[64:65], s[14:15], v64, s59, v[112:113]
	v_pk_add_f32 v[60:61], v[60:61], 1.0 op_sel_hi:[1,0]
	v_lshl_add_u64 v[64:65], v[64:65], 0, v[114:115]
	v_rcp_f32_e32 v60, v60
	v_rcp_f32_e32 v61, v61
	global_store_dwordx4 v[64:65], v[72:75], off sc1
	v_add_u32_e32 v65, 0x80, v167
	v_mul_f32_e32 v64, v142, v142
	v_pk_mul_f32 v[58:59], v[62:63], v[58:59]
	v_pk_mul_f32 v[62:63], v[64:65], v[68:69] op_sel_hi:[0,1]
	v_pk_mul_f32 v[56:57], v[56:57], v[62:63]
	v_pk_mul_f32 v[62:63], v[52:53], v[66:67] op_sel_hi:[1,0]
	v_pk_mul_f32 v[60:61], v[64:65], v[60:61] op_sel_hi:[0,1]
	v_exp_f32_e32 v62, v62
	v_exp_f32_e32 v63, v63
	v_pk_mul_f32 v[58:59], v[58:59], v[60:61]
	v_pk_mul_f32 v[60:61], v[54:55], v[66:67] op_sel_hi:[1,0]
	v_cvt_pk_bf16_f32 v56, v56, v57
	v_cvt_pk_bf16_f32 v57, v58, v59
	v_pk_add_f32 v[58:59], v[62:63], 1.0 op_sel_hi:[1,0]
	v_exp_f32_e32 v60, v60
	v_exp_f32_e32 v61, v61
	v_rcp_f32_e32 v58, v58
	v_rcp_f32_e32 v59, v59
	v_pk_mul_f32 v[48:49], v[52:53], v[48:49]
	v_pk_add_f32 v[52:53], v[60:61], 1.0 op_sel_hi:[1,0]
	v_pk_mul_f32 v[50:51], v[54:55], v[50:51]
	v_rcp_f32_e32 v52, v52
	v_rcp_f32_e32 v53, v53
	v_pk_mul_f32 v[54:55], v[64:65], v[58:59] op_sel_hi:[0,1]
	v_pk_mul_f32 v[48:49], v[48:49], v[54:55]
	v_pk_mul_f32 v[40:41], v[44:45], v[40:41]
	v_cvt_pk_bf16_f32 v58, v48, v49
	v_pk_mul_f32 v[48:49], v[64:65], v[52:53] op_sel_hi:[0,1]
	v_pk_mul_f32 v[48:49], v[50:51], v[48:49]
	v_mul_f32_e32 v50, 0xbfb8aa3b, v143
	v_pk_mul_f32 v[52:53], v[44:45], v[50:51] op_sel_hi:[1,0]
	v_pk_mul_f32 v[44:45], v[46:47], v[50:51] op_sel_hi:[1,0]
	v_exp_f32_e32 v52, v52
	v_exp_f32_e32 v53, v53
	v_exp_f32_e32 v44, v44
	v_exp_f32_e32 v45, v45
	v_cvt_pk_bf16_f32 v59, v48, v49
	v_pk_add_f32 v[52:53], v[52:53], 1.0 op_sel_hi:[1,0]
	v_mad_i64_i32 v[48:49], s[14:15], v65, s59, v[112:113]
	v_rcp_f32_e32 v52, v52
	v_rcp_f32_e32 v53, v53
	v_pk_add_f32 v[44:45], v[44:45], 1.0 op_sel_hi:[1,0]
	v_lshl_add_u64 v[48:49], v[48:49], 0, v[114:115]
	v_rcp_f32_e32 v44, v44
	v_rcp_f32_e32 v45, v45
	global_store_dwordx4 v[48:49], v[56:59], off sc1
	v_mul_f32_e32 v48, v143, v143
	v_pk_mul_f32 v[42:43], v[46:47], v[42:43]
; __device__ __forceinline__ unsigned cvt_pk_bf16(float lo, float hi) { unsigned r; asm volatile("v_cvt_pk_bf16_f32 %0, %1, %2" : "=v"(r) : "v"(lo), "v"(hi)); return r; }
;     __device__ __forceinline__ void operator()(const f32x4 (&acc)[2][2][4][2], const Unit& u, int ui, int wr, int wc, int fr, int fq) const {
;     ...
;             for (int m = 0; m < 4; ++m) { const float r = rs[ai][m]; const int row = row0 + ai * HALF + m * 16;
;                 const float c1 = r * -1.44269504089f, r2 = r * r; u32x4 w;
; #pragma unroll
;                 for (int n = 0; n < 2; ++n)
; #pragma unroll
;                     for (int p = 0; p < 2; ++p) { const f32x2 g = (f32x2){acc[ai][0][m][n][2 * p], acc[ai][0][m][n][2 * p + 1]}, uu = (f32x2){acc[ai][1][m][n][2 * p], acc[ai][1][m][n][2 * p + 1]};
;                         const f32x2 t = g * c1; f32x2 d; d.x = __builtin_amdgcn_exp2f(t.x); d.y = __builtin_amdgcn_exp2f(t.y); d = d + 1.0f;
;                         f32x2 q; q.x = __builtin_amdgcn_rcpf(d.x); q.y = __builtin_amdgcn_rcpf(d.y);
;                         const f32x2 hh = (g * uu) * (q * r2); w[2 * n + p] = cvt_pk_bf16(hh.x, hh.y); }
;                 __builtin_nontemporal_store(w, (u32x4*)(H + (size_t)row * ldh + col0)); }
	v_pk_mul_f32 v[46:47], v[48:49], v[52:53] op_sel_hi:[0,1]
	v_pk_mul_f32 v[40:41], v[40:41], v[46:47]
	v_pk_mul_f32 v[46:47], v[36:37], v[50:51] op_sel_hi:[1,0]
	v_pk_mul_f32 v[44:45], v[48:49], v[44:45] op_sel_hi:[0,1]
	v_exp_f32_e32 v46, v46
	v_exp_f32_e32 v47, v47
	v_pk_mul_f32 v[42:43], v[42:43], v[44:45]
	v_pk_mul_f32 v[44:45], v[38:39], v[50:51] op_sel_hi:[1,0]
	v_cvt_pk_bf16_f32 v40, v40, v41
	v_cvt_pk_bf16_f32 v41, v42, v43
	v_pk_add_f32 v[42:43], v[46:47], 1.0 op_sel_hi:[1,0]
	v_exp_f32_e32 v44, v44
	v_exp_f32_e32 v45, v45
	v_rcp_f32_e32 v42, v42
	v_rcp_f32_e32 v43, v43
	v_pk_mul_f32 v[32:33], v[36:37], v[32:33]
	v_pk_add_f32 v[36:37], v[44:45], 1.0 op_sel_hi:[1,0]
	v_pk_mul_f32 v[34:35], v[38:39], v[34:35]
	v_rcp_f32_e32 v36, v36
	v_rcp_f32_e32 v37, v37
	v_pk_mul_f32 v[38:39], v[48:49], v[42:43] op_sel_hi:[0,1]
	v_pk_mul_f32 v[32:33], v[32:33], v[38:39]
	v_pk_mul_f32 v[24:25], v[28:29], v[24:25]
	v_cvt_pk_bf16_f32 v42, v32, v33
	v_pk_mul_f32 v[32:33], v[48:49], v[36:37] op_sel_hi:[0,1]
	v_pk_mul_f32 v[32:33], v[34:35], v[32:33]
	v_mul_f32_e32 v34, 0xbfb8aa3b, v140
	v_pk_mul_f32 v[36:37], v[28:29], v[34:35] op_sel_hi:[1,0]
	v_pk_mul_f32 v[28:29], v[30:31], v[34:35] op_sel_hi:[1,0]
	v_exp_f32_e32 v36, v36
	v_exp_f32_e32 v37, v37
	v_exp_f32_e32 v28, v28
	v_exp_f32_e32 v29, v29
	v_cvt_pk_bf16_f32 v43, v32, v33
	v_pk_add_f32 v[36:37], v[36:37], 1.0 op_sel_hi:[1,0]
	v_add_u32_e32 v32, 0x90, v167
	v_rcp_f32_e32 v36, v36
	v_rcp_f32_e32 v37, v37
	v_mad_i64_i32 v[32:33], s[14:15], v32, s59, v[112:113]
	v_pk_add_f32 v[28:29], v[28:29], 1.0 op_sel_hi:[1,0]
	v_lshl_add_u64 v[32:33], v[32:33], 0, v[114:115]
	v_rcp_f32_e32 v28, v28
	v_rcp_f32_e32 v29, v29
	global_store_dwordx4 v[32:33], v[40:43], off sc1
	v_mul_f32_e32 v32, v140, v140
	v_pk_mul_f32 v[26:27], v[30:31], v[26:27]
	v_pk_mul_f32 v[30:31], v[32:33], v[36:37] op_sel_hi:[0,1]
	v_pk_mul_f32 v[24:25], v[24:25], v[30:31]
	v_pk_mul_f32 v[30:31], v[20:21], v[34:35] op_sel_hi:[1,0]
	v_pk_mul_f32 v[28:29], v[32:33], v[28:29] op_sel_hi:[0,1]
	v_exp_f32_e32 v30, v30
	v_exp_f32_e32 v31, v31
	v_pk_mul_f32 v[26:27], v[26:27], v[28:29]
	v_pk_mul_f32 v[28:29], v[22:23], v[34:35] op_sel_hi:[1,0]
	v_cvt_pk_bf16_f32 v24, v24, v25
	v_cvt_pk_bf16_f32 v25, v26, v27
	v_pk_add_f32 v[26:27], v[30:31], 1.0 op_sel_hi:[1,0]
	v_exp_f32_e32 v28, v28
	v_exp_f32_e32 v29, v29
	v_rcp_f32_e32 v26, v26
	v_rcp_f32_e32 v27, v27
	v_pk_mul_f32 v[16:17], v[20:21], v[16:17]
	v_pk_add_f32 v[20:21], v[28:29], 1.0 op_sel_hi:[1,0]
	v_pk_mul_f32 v[18:19], v[22:23], v[18:19]
	v_rcp_f32_e32 v20, v20
	v_rcp_f32_e32 v21, v21
	v_pk_mul_f32 v[22:23], v[32:33], v[26:27] op_sel_hi:[0,1]
	v_pk_mul_f32 v[16:17], v[16:17], v[22:23]
	v_pk_mul_f32 v[8:9], v[12:13], v[8:9]
	v_cvt_pk_bf16_f32 v26, v16, v17
	v_pk_mul_f32 v[16:17], v[32:33], v[20:21] op_sel_hi:[0,1]
	v_pk_mul_f32 v[16:17], v[18:19], v[16:17]
	v_mul_f32_e32 v18, 0xbfb8aa3b, v141
	v_pk_mul_f32 v[20:21], v[12:13], v[18:19] op_sel_hi:[1,0]
	v_pk_mul_f32 v[12:13], v[14:15], v[18:19] op_sel_hi:[1,0]
	v_exp_f32_e32 v20, v20
	v_exp_f32_e32 v21, v21
	v_exp_f32_e32 v12, v12
	v_exp_f32_e32 v13, v13
	v_cvt_pk_bf16_f32 v27, v16, v17
	v_pk_add_f32 v[20:21], v[20:21], 1.0 op_sel_hi:[1,0]
	v_add_u32_e32 v16, 0xa0, v167
	v_rcp_f32_e32 v20, v20
	v_rcp_f32_e32 v21, v21
	v_mad_i64_i32 v[16:17], s[14:15], v16, s59, v[112:113]
	v_pk_add_f32 v[12:13], v[12:13], 1.0 op_sel_hi:[1,0]
	v_lshl_add_u64 v[16:17], v[16:17], 0, v[114:115]
	v_rcp_f32_e32 v12, v12
	v_rcp_f32_e32 v13, v13
	global_store_dwordx4 v[16:17], v[24:27], off sc1
	v_mul_f32_e32 v16, v141, v141
	v_pk_mul_f32 v[10:11], v[14:15], v[10:11]
	v_pk_mul_f32 v[14:15], v[16:17], v[20:21] op_sel_hi:[0,1]
	v_pk_mul_f32 v[8:9], v[8:9], v[14:15]
	v_pk_mul_f32 v[14:15], v[4:5], v[18:19] op_sel_hi:[1,0]
	v_pk_mul_f32 v[12:13], v[16:17], v[12:13] op_sel_hi:[0,1]
	v_exp_f32_e32 v14, v14
	v_exp_f32_e32 v15, v15
	v_pk_mul_f32 v[10:11], v[10:11], v[12:13]
	v_pk_mul_f32 v[12:13], v[6:7], v[18:19] op_sel_hi:[1,0]
	v_cvt_pk_bf16_f32 v8, v8, v9
	v_cvt_pk_bf16_f32 v9, v10, v11
	v_pk_add_f32 v[10:11], v[14:15], 1.0 op_sel_hi:[1,0]
	v_exp_f32_e32 v12, v12
	v_exp_f32_e32 v13, v13
	v_rcp_f32_e32 v10, v10
	v_rcp_f32_e32 v11, v11
	v_pk_mul_f32 v[0:1], v[4:5], v[0:1]
	v_pk_add_f32 v[4:5], v[12:13], 1.0 op_sel_hi:[1,0]
	v_pk_mul_f32 v[2:3], v[6:7], v[2:3]
	v_rcp_f32_e32 v4, v4
	v_rcp_f32_e32 v5, v5
	v_pk_mul_f32 v[6:7], v[16:17], v[10:11] op_sel_hi:[0,1]
	v_pk_mul_f32 v[0:1], v[0:1], v[6:7]
	s_andn2_b64 vcc, exec, s[8:9]
	v_cvt_pk_bf16_f32 v10, v0, v1
	v_pk_mul_f32 v[0:1], v[16:17], v[4:5] op_sel_hi:[0,1]
	v_pk_mul_f32 v[0:1], v[2:3], v[0:1]
	s_mov_b64 s[8:9], -1
	v_cvt_pk_bf16_f32 v11, v0, v1
	v_add_u32_e32 v0, 0xb0, v167
	v_mad_i64_i32 v[0:1], s[14:15], v0, s59, v[112:113]
	v_lshl_add_u64 v[0:1], v[0:1], 0, v[114:115]
	global_store_dwordx4 v[0:1], v[8:11], off sc1
	s_cbranch_vccnz .LBB0_442
	s_andn2_b64 vcc, exec, s[0:1]
	s_cbranch_vccnz .LBB0_441
	s_barrier
	s_branch .LBB0_441
